# GU/WIN unit seam: trailing half re-creates the stagger after its unit-header arithmetic instead of before it
# baseline (speedup 1.0000x reference)
; #define PG8_STAGE(bufoff, gbase, voff) do { _Pragma("unroll") for (int _i = 0; _i < 2; ++_i) \
;         __builtin_amdgcn_global_load_lds((const unsigned*)((const char*)(gbase) + (voff)[_i]), (PG8_LAS unsigned*)(lds + (bufoff) + ldsw + _i * 8192), 16, 0, 0); } while (0)
; #define PG8_LDA(dst, b, h) do { _Pragma("unroll") for (int m = 0; m < 4; ++m) _Pragma("unroll") for (int k = 0; k < 2; ++k) dst[m][k] = *(const PG8_LAS bf16x8*)(lds + PG8_SA(b, h) + aoff + m * 2048 + k * 1024); } while (0)
; #define PG8_LDB(dst, b, h) do { _Pragma("unroll") for (int n = 0; n < 2; ++n) _Pragma("unroll") for (int k = 0; k < 2; ++k) dst[n][k] = *(const PG8_LAS bf16x8*)(lds + PG8_SB(b, h) + boff + n * 2048 + k * 1024); } while (0)
; #define PG8_WAIT_V(n) asm volatile("s_waitcnt vmcnt(" #n ")" ::: "memory")
; #define PG8_WAIT_L(n) asm volatile("s_waitcnt lgkmcnt(" #n ")" ::: "memory")
; template <class Epi, class Sched, bool ALIGN_EPI = false, bool SP2 = false>
; __device__ __forceinline__ void gemm_phase(PG8_LAS unsigned char* lds, const Gemm g, const Sched& S, const Epi& E) {
;     ...
;         const bool has_next = S.next(ui + 1, nxt);
;         const char* nA = has_next ? (const char*)g.A + (size_t)nxt.pm * tstep : cA; const char* nB = has_next ? (const char*)g.Bt + (size_t)nxt.pn * tstep : cB;
;         for (int t = 0; t < nt; t += 2) {
;             const bool last = (t == nt - 2);
;             const char* a1 = cA + (size_t)(t + 1) * kstep;
;             const char* a2 = last ? nA : cA + (size_t)(t + 2) * kstep; const char* b2 = last ? nB : cB + (size_t)(t + 2) * kstep;
;             const char* a3 = a2 + kstep; const char* b3 = b2 + kstep;
;             if (last && has_next) S.a_ready(nxt);
;             if (last) E.pre(cur, wid, lane);
;             if constexpr (SP2) {
;             PG8_LDB(B0, 0, 0); PG8_LDB(B1, 0, 1); PG8_SCHED; PG8_LDA(At, 0, 0); PG8_STAGE(PG8_SA(1, 1), a1 + hstep, voffA);
;             PG8_WAIT_V(8); PG8_WAIT_L(0); PG8_BAR; PG8_MMA(0, 0, At, B0); PG8_MMA(0, 1, At, B1); PG8_BAR; PG8_SCHED;
;             PG8_LDA(At, 0, 1); PG8_STAGE(PG8_SB(0, 0), b2, voffB); PG8_STAGE(PG8_SB(0, 1), b2 + hstep, voffB); PG8_STAGE(PG8_SA(0, 0), a2, voffA);
;             PG8_WAIT_V(8); PG8_WAIT_L(0); PG8_BAR; PG8_MMA(1, 0, At, B0); PG8_MMA(1, 1, At, B1); PG8_BAR; PG8_SCHED;
;     ...
;         if constexpr (ALIGN_EPI) { if (wr == 1) PG8_BAR; }
.LBB0_243:
	s_ashr_i32 s49, s48, 31
	s_lshl_b64 s[6:7], s[48:49], 19
	s_add_u32 s50, s10, s6
	s_addc_u32 s51, s11, s7
	s_and_b64 s[6:7], s[36:37], exec
	s_cselect_b32 s38, s51, s5
	s_cselect_b32 s39, s50, s4
	s_ashr_i32 s47, s46, 31
	s_lshl_b64 s[6:7], s[46:47], 19
	s_add_u32 s52, s12, s6
	v_readlane_b32 s6, v255, 3
	s_addc_u32 s53, s6, s7
	s_and_b64 s[6:7], s[36:37], exec
	s_cselect_b32 s49, s53, s1
	s_cselect_b32 s55, s52, s0
	s_lshl_b32 s47, s56, 8
	v_add_u32_e32 v0, s47, v198
	v_ashrrev_i32_e32 v1, 31, v0
	v_lshlrev_b64 v[2:3], 6, v[0:1]
	v_or_b32_e32 v0, 16, v0
	v_ashrrev_i32_e32 v1, 31, v0
	s_add_u32 s4, s4, 0x40080
	v_lshlrev_b64 v[0:1], 6, v[0:1]
	s_addc_u32 s5, s5, 0
	v_lshl_add_u64 v[128:129], v[160:161], 0, v[0:1]
	s_add_u32 s56, s0, 0x100
	v_lshl_add_u64 v[130:131], v[160:161], 0, v[2:3]
	s_addc_u32 s57, s1, 0
	s_mov_b32 s58, -2
	s_cmp_gt_u32 s34, 1
	s_cselect_b64 vcc, s[40:41], 0
	s_cbranch_vccz .Lwin_nostag
	s_barrier
.Lwin_nostag:
	s_branch .Lwin_peel
.LBB0_244:
	s_add_u32 s6, s4, 0xfffc0080
	s_addc_u32 s7, s5, -1
	s_and_b64 s[0:1], s[0:1], exec
	s_cselect_b32 s7, s38, s7
	s_cselect_b32 s6, s39, s6
	s_cselect_b32 s1, s49, s57
	s_cselect_b32 s0, s55, s56
	s_add_i32 s59, 0, 0x10000
	v_add_u32_e32 v144, s59, v197
	s_add_i32 s62, 0, 0x14000
	ds_read_b128 v[132:135], v144
	ds_read_b128 v[136:139], v144 offset:1024
	ds_read_b128 v[140:143], v144 offset:2048
	ds_read_b128 v[202:205], v144 offset:3072
	v_add_u32_e32 v144, s62, v197
	ds_read_b128 v[206:209], v144
	ds_read_b128 v[210:213], v144 offset:1024
	ds_read_b128 v[214:217], v144 offset:2048
	ds_read_b128 v[218:221], v144 offset:3072
	v_lshl_add_u64 v[172:173], s[4:5], 0, v[166:167]
	s_add_i32 m0, s25, 0xc000
	ds_read_b128 v[222:225], v199
	ds_read_b128 v[226:229], v199 offset:1024
	ds_read_b128 v[230:233], v199 offset:2048
	ds_read_b128 v[234:237], v199 offset:3072
	ds_read_b128 v[238:241], v199 offset:4096
	ds_read_b128 v[242:245], v199 offset:5120
	ds_read_b128 v[246:249], v199 offset:6144
	ds_read_b128 v[180:183], v199 offset:7168
	global_load_lds_dwordx4 v[172:173], off
	v_lshl_add_u64 v[172:173], s[4:5], 0, v[168:169]
	s_add_i32 m0, s25, 0xe000
	s_nop 0
	global_load_lds_dwordx4 v[172:173], off
	s_waitcnt vmcnt(8)
	s_waitcnt lgkmcnt(0)
	.p2alignl 3, 3212836864
	s_setprio 1
	s_barrier
	v_mfma_f32_16x16x32_bf16 v[124:127], v[132:135], v[222:225], v[124:127]
	v_mfma_f32_16x16x32_bf16 v[120:123], v[140:143], v[222:225], v[120:123]
	v_mfma_f32_16x16x32_bf16 v[108:111], v[132:135], v[230:233], v[108:111]
	v_mfma_f32_16x16x32_bf16 v[104:107], v[140:143], v[230:233], v[104:107]
	v_mfma_f32_16x16x32_bf16 v[92:95], v[132:135], v[238:241], v[92:95]
	v_mfma_f32_16x16x32_bf16 v[88:91], v[140:143], v[238:241], v[88:91]
	v_mfma_f32_16x16x32_bf16 v[76:79], v[132:135], v[246:249], v[76:79]
	v_mfma_f32_16x16x32_bf16 v[72:75], v[140:143], v[246:249], v[72:75]
	v_mfma_f32_16x16x32_bf16 v[124:127], v[136:139], v[226:229], v[124:127]
	v_mfma_f32_16x16x32_bf16 v[120:123], v[202:205], v[226:229], v[120:123]
	v_mfma_f32_16x16x32_bf16 v[108:111], v[136:139], v[234:237], v[108:111]
	v_mfma_f32_16x16x32_bf16 v[104:107], v[202:205], v[234:237], v[104:107]
	v_mfma_f32_16x16x32_bf16 v[92:95], v[136:139], v[242:245], v[92:95]
	v_mfma_f32_16x16x32_bf16 v[88:91], v[202:205], v[242:245], v[88:91]
	v_mfma_f32_16x16x32_bf16 v[76:79], v[136:139], v[180:183], v[76:79]
	v_mfma_f32_16x16x32_bf16 v[72:75], v[202:205], v[180:183], v[72:75]
	s_setprio 0
	s_setprio 1
	v_mfma_f32_16x16x32_bf16 v[116:119], v[206:209], v[222:225], v[116:119]
	v_mfma_f32_16x16x32_bf16 v[112:115], v[214:217], v[222:225], v[112:115]
	v_mfma_f32_16x16x32_bf16 v[100:103], v[206:209], v[230:233], v[100:103]
	v_mfma_f32_16x16x32_bf16 v[96:99], v[214:217], v[230:233], v[96:99]
	v_mfma_f32_16x16x32_bf16 v[84:87], v[206:209], v[238:241], v[84:87]
	v_mfma_f32_16x16x32_bf16 v[80:83], v[214:217], v[238:241], v[80:83]
	v_mfma_f32_16x16x32_bf16 v[68:71], v[206:209], v[246:249], v[68:71]
	v_mfma_f32_16x16x32_bf16 v[64:67], v[214:217], v[246:249], v[64:67]
	v_mfma_f32_16x16x32_bf16 v[116:119], v[210:213], v[226:229], v[116:119]
	v_mfma_f32_16x16x32_bf16 v[112:115], v[218:221], v[226:229], v[112:115]
	v_mfma_f32_16x16x32_bf16 v[100:103], v[210:213], v[234:237], v[100:103]
	v_mfma_f32_16x16x32_bf16 v[96:99], v[218:221], v[234:237], v[96:99]
	v_mfma_f32_16x16x32_bf16 v[84:87], v[210:213], v[242:245], v[84:87]
	v_mfma_f32_16x16x32_bf16 v[80:83], v[218:221], v[242:245], v[80:83]
	v_mfma_f32_16x16x32_bf16 v[68:71], v[210:213], v[180:183], v[68:71]
	v_mfma_f32_16x16x32_bf16 v[64:67], v[218:221], v[180:183], v[64:67]
	s_barrier
	s_setprio 0
	s_add_i32 s59, s59, s24
	v_lshl_add_u64 v[172:173], s[0:1], 0, v[154:155]
	s_mov_b32 m0, s59
	ds_read_b128 v[180:183], v199 offset:16384
	ds_read_b128 v[222:225], v199 offset:17408
	ds_read_b128 v[226:229], v199 offset:18432
	ds_read_b128 v[230:233], v199 offset:19456
	ds_read_b128 v[234:237], v199 offset:20480
	ds_read_b128 v[238:241], v199 offset:21504
	ds_read_b128 v[242:245], v199 offset:22528
	ds_read_b128 v[246:249], v199 offset:23552
	global_load_lds_dwordx4 v[172:173], off
	s_add_i32 m0, s59, 0x2000
	s_add_u32 s60, s0, 0x40000
	v_lshl_add_u64 v[184:185], s[0:1], 0, v[150:151]
	s_addc_u32 s61, s1, 0
	s_add_i32 s59, s62, s24
	global_load_lds_dwordx4 v[184:185], off
	v_lshl_add_u64 v[186:187], s[60:61], 0, v[154:155]
	s_mov_b32 m0, s59
	v_lshl_add_u64 v[188:189], s[6:7], 0, v[152:153]
	global_load_lds_dwordx4 v[186:187], off
	v_lshl_add_u64 v[186:187], s[60:61], 0, v[150:151]
	s_add_i32 m0, s59, 0x2000
	s_nop 0
	global_load_lds_dwordx4 v[186:187], off
	v_lshl_add_u64 v[186:187], s[6:7], 0, v[156:157]
	s_mov_b32 m0, s25
	s_nop 0
	global_load_lds_dwordx4 v[186:187], off
	s_mov_b32 m0, s26
	s_nop 0
	global_load_lds_dwordx4 v[188:189], off
	s_waitcnt vmcnt(8)
	s_waitcnt lgkmcnt(0)
	.p2alignl 3, 3212836864
	s_setprio 1
	s_barrier
; #define PG8_STAGE(bufoff, gbase, voff) do { _Pragma("unroll") for (int _i = 0; _i < 2; ++_i) \
;         __builtin_amdgcn_global_load_lds((const unsigned*)((const char*)(gbase) + (voff)[_i]), (PG8_LAS unsigned*)(lds + (bufoff) + ldsw + _i * 8192), 16, 0, 0); } while (0)
; #define PG8_LDA(dst, b, h) do { _Pragma("unroll") for (int m = 0; m < 4; ++m) _Pragma("unroll") for (int k = 0; k < 2; ++k) dst[m][k] = *(const PG8_LAS bf16x8*)(lds + PG8_SA(b, h) + aoff + m * 2048 + k * 1024); } while (0)
; #define PG8_LDB(dst, b, h) do { _Pragma("unroll") for (int n = 0; n < 2; ++n) _Pragma("unroll") for (int k = 0; k < 2; ++k) dst[n][k] = *(const PG8_LAS bf16x8*)(lds + PG8_SB(b, h) + boff + n * 2048 + k * 1024); } while (0)
; #define PG8_MMA(ai, bj, At, Bt) do { __builtin_amdgcn_s_setprio(1); _Pragma("unroll") for (int m = 0; m < 4; ++m) _Pragma("unroll") for (int n = 0; n < 2; ++n) _Pragma("unroll") for (int k = 0; k < 2; ++k) \
;         acc[ai][bj][m][n] = __builtin_amdgcn_mfma_f32_16x16x32_bf16(Bt[n][k], At[m][k], acc[ai][bj][m][n], 0, 0, 0); __builtin_amdgcn_s_setprio(0); } while (0)
; #define PG8_WAIT_V(n) asm volatile("s_waitcnt vmcnt(" #n ")" ::: "memory")
; #define PG8_WAIT_L(n) asm volatile("s_waitcnt lgkmcnt(" #n ")" ::: "memory")
; #define PG8_BAR __builtin_amdgcn_s_barrier()
; template <class Epi, class Sched, bool ALIGN_EPI = false, bool SP2 = false>
; __device__ __forceinline__ void gemm_phase(PG8_LAS unsigned char* lds, const Gemm g, const Sched& S, const Epi& E) {
;     ...
;             PG8_WAIT_V(8); PG8_WAIT_L(0); PG8_BAR; PG8_MMA(0, 0, At, B0); PG8_MMA(0, 1, At, B1); PG8_BAR; PG8_SCHED;
;             PG8_LDA(At, 0, 1); PG8_STAGE(PG8_SB(0, 0), b2, voffB); PG8_STAGE(PG8_SB(0, 1), b2 + hstep, voffB); PG8_STAGE(PG8_SA(0, 0), a2, voffA);
;             PG8_WAIT_V(8); PG8_WAIT_L(0); PG8_BAR; PG8_MMA(1, 0, At, B0); PG8_MMA(1, 1, At, B1); PG8_BAR; PG8_SCHED;
;             PG8_LDB(B0, 1, 0); PG8_LDB(B1, 1, 1); PG8_SCHED; PG8_LDA(At, 1, 0); PG8_STAGE(PG8_SA(0, 1), a2 + hstep, voffA);
;             PG8_WAIT_V(8); PG8_WAIT_L(0); PG8_BAR; PG8_MMA(0, 0, At, B0); PG8_MMA(0, 1, At, B1); PG8_BAR; PG8_SCHED;
;             PG8_LDA(At, 1, 1); PG8_STAGE(PG8_SB(1, 0), b3, voffB); PG8_STAGE(PG8_SB(1, 1), b3 + hstep, voffB); PG8_STAGE(PG8_SA(1, 0), a3, voffA);
;             PG8_WAIT_V(8); PG8_WAIT_L(0); PG8_BAR; PG8_MMA(1, 0, At, B0); PG8_MMA(1, 1, At, B1); PG8_BAR; PG8_SCHED;
	v_mfma_f32_16x16x32_bf16 v[60:63], v[132:135], v[180:183], v[60:63]
	v_mfma_f32_16x16x32_bf16 v[56:59], v[140:143], v[180:183], v[56:59]
	v_mfma_f32_16x16x32_bf16 v[44:47], v[132:135], v[226:229], v[44:47]
	v_mfma_f32_16x16x32_bf16 v[40:43], v[140:143], v[226:229], v[40:43]
	v_mfma_f32_16x16x32_bf16 v[28:31], v[132:135], v[234:237], v[28:31]
	v_mfma_f32_16x16x32_bf16 v[24:27], v[140:143], v[234:237], v[24:27]
	v_mfma_f32_16x16x32_bf16 v[12:15], v[132:135], v[242:245], v[12:15]
	v_mfma_f32_16x16x32_bf16 v[8:11], v[140:143], v[242:245], v[8:11]
	v_mfma_f32_16x16x32_bf16 v[60:63], v[136:139], v[222:225], v[60:63]
	v_mfma_f32_16x16x32_bf16 v[56:59], v[202:205], v[222:225], v[56:59]
	v_mfma_f32_16x16x32_bf16 v[44:47], v[136:139], v[230:233], v[44:47]
	v_mfma_f32_16x16x32_bf16 v[40:43], v[202:205], v[230:233], v[40:43]
	v_mfma_f32_16x16x32_bf16 v[28:31], v[136:139], v[238:241], v[28:31]
	v_mfma_f32_16x16x32_bf16 v[24:27], v[202:205], v[238:241], v[24:27]
	v_mfma_f32_16x16x32_bf16 v[12:15], v[136:139], v[246:249], v[12:15]
	v_mfma_f32_16x16x32_bf16 v[8:11], v[202:205], v[246:249], v[8:11]
	s_setprio 0
	s_setprio 1
	v_mfma_f32_16x16x32_bf16 v[52:55], v[206:209], v[180:183], v[52:55]
	v_mfma_f32_16x16x32_bf16 v[48:51], v[214:217], v[180:183], v[48:51]
	v_mfma_f32_16x16x32_bf16 v[36:39], v[206:209], v[226:229], v[36:39]
	v_mfma_f32_16x16x32_bf16 v[32:35], v[214:217], v[226:229], v[32:35]
	v_mfma_f32_16x16x32_bf16 v[20:23], v[206:209], v[234:237], v[20:23]
	v_mfma_f32_16x16x32_bf16 v[16:19], v[214:217], v[234:237], v[16:19]
	v_mfma_f32_16x16x32_bf16 v[4:7], v[206:209], v[242:245], v[4:7]
	v_mfma_f32_16x16x32_bf16 v[0:3], v[214:217], v[242:245], v[0:3]
	v_mfma_f32_16x16x32_bf16 v[52:55], v[210:213], v[222:225], v[52:55]
	v_mfma_f32_16x16x32_bf16 v[48:51], v[218:221], v[222:225], v[48:51]
	v_mfma_f32_16x16x32_bf16 v[36:39], v[210:213], v[230:233], v[36:39]
	v_mfma_f32_16x16x32_bf16 v[32:35], v[218:221], v[230:233], v[32:35]
	v_mfma_f32_16x16x32_bf16 v[20:23], v[210:213], v[238:241], v[20:23]
	v_mfma_f32_16x16x32_bf16 v[16:19], v[218:221], v[238:241], v[16:19]
	v_mfma_f32_16x16x32_bf16 v[4:7], v[210:213], v[246:249], v[4:7]
	v_mfma_f32_16x16x32_bf16 v[0:3], v[218:221], v[246:249], v[0:3]
	s_barrier
	s_setprio 0
	s_add_i32 s59, 0, 0x18000
	v_add_u32_e32 v144, s59, v197
	s_add_i32 s60, 0, 0x1c000
	ds_read_b128 v[132:135], v144
	ds_read_b128 v[136:139], v144 offset:1024
	ds_read_b128 v[140:143], v144 offset:2048
	ds_read_b128 v[180:183], v144 offset:3072
	v_add_u32_e32 v144, s60, v197
	ds_read_b128 v[202:205], v144
	ds_read_b128 v[206:209], v144 offset:1024
	ds_read_b128 v[210:213], v144 offset:2048
	ds_read_b128 v[214:217], v144 offset:3072
	s_add_u32 s6, s6, 0x40000
	s_addc_u32 s7, s7, 0
	s_mov_b32 m0, s27
	v_lshl_add_u64 v[190:191], s[6:7], 0, v[156:157]
	ds_read_b128 v[218:221], v199 offset:32768
	ds_read_b128 v[222:225], v199 offset:33792
	ds_read_b128 v[226:229], v199 offset:34816
	ds_read_b128 v[230:233], v199 offset:35840
	ds_read_b128 v[234:237], v199 offset:36864
	ds_read_b128 v[238:241], v199 offset:37888
	ds_read_b128 v[242:245], v199 offset:38912
	ds_read_b128 v[246:249], v199 offset:39936
	global_load_lds_dwordx4 v[190:191], off
	v_lshl_add_u64 v[190:191], s[6:7], 0, v[152:153]
	s_mov_b32 m0, s28
	s_nop 0
	global_load_lds_dwordx4 v[190:191], off
	s_waitcnt vmcnt(8)
	s_waitcnt lgkmcnt(0)
	.p2alignl 3, 3212836864
	s_setprio 1
	s_barrier
	v_mfma_f32_16x16x32_bf16 v[124:127], v[132:135], v[218:221], v[124:127]
	v_mfma_f32_16x16x32_bf16 v[120:123], v[140:143], v[218:221], v[120:123]
	v_mfma_f32_16x16x32_bf16 v[108:111], v[132:135], v[226:229], v[108:111]
	v_mfma_f32_16x16x32_bf16 v[104:107], v[140:143], v[226:229], v[104:107]
	v_mfma_f32_16x16x32_bf16 v[92:95], v[132:135], v[234:237], v[92:95]
	v_mfma_f32_16x16x32_bf16 v[88:91], v[140:143], v[234:237], v[88:91]
	v_mfma_f32_16x16x32_bf16 v[76:79], v[132:135], v[242:245], v[76:79]
	v_mfma_f32_16x16x32_bf16 v[72:75], v[140:143], v[242:245], v[72:75]
	v_mfma_f32_16x16x32_bf16 v[124:127], v[136:139], v[222:225], v[124:127]
	v_mfma_f32_16x16x32_bf16 v[120:123], v[180:183], v[222:225], v[120:123]
	v_mfma_f32_16x16x32_bf16 v[108:111], v[136:139], v[230:233], v[108:111]
	v_mfma_f32_16x16x32_bf16 v[104:107], v[180:183], v[230:233], v[104:107]
	v_mfma_f32_16x16x32_bf16 v[92:95], v[136:139], v[238:241], v[92:95]
	v_mfma_f32_16x16x32_bf16 v[88:91], v[180:183], v[238:241], v[88:91]
	v_mfma_f32_16x16x32_bf16 v[76:79], v[136:139], v[246:249], v[76:79]
	v_mfma_f32_16x16x32_bf16 v[72:75], v[180:183], v[246:249], v[72:75]
	s_setprio 0
	s_setprio 1
	v_mfma_f32_16x16x32_bf16 v[116:119], v[202:205], v[218:221], v[116:119]
	v_mfma_f32_16x16x32_bf16 v[112:115], v[210:213], v[218:221], v[112:115]
	v_mfma_f32_16x16x32_bf16 v[100:103], v[202:205], v[226:229], v[100:103]
	v_mfma_f32_16x16x32_bf16 v[96:99], v[210:213], v[226:229], v[96:99]
	v_mfma_f32_16x16x32_bf16 v[84:87], v[202:205], v[234:237], v[84:87]
	v_mfma_f32_16x16x32_bf16 v[80:83], v[210:213], v[234:237], v[80:83]
	v_mfma_f32_16x16x32_bf16 v[68:71], v[202:205], v[242:245], v[68:71]
	v_mfma_f32_16x16x32_bf16 v[64:67], v[210:213], v[242:245], v[64:67]
	v_mfma_f32_16x16x32_bf16 v[116:119], v[206:209], v[222:225], v[116:119]
	v_mfma_f32_16x16x32_bf16 v[112:115], v[214:217], v[222:225], v[112:115]
	v_mfma_f32_16x16x32_bf16 v[100:103], v[206:209], v[230:233], v[100:103]
	v_mfma_f32_16x16x32_bf16 v[96:99], v[214:217], v[230:233], v[96:99]
	v_mfma_f32_16x16x32_bf16 v[84:87], v[206:209], v[238:241], v[84:87]
	v_mfma_f32_16x16x32_bf16 v[80:83], v[214:217], v[238:241], v[80:83]
	v_mfma_f32_16x16x32_bf16 v[68:71], v[206:209], v[246:249], v[68:71]
	v_mfma_f32_16x16x32_bf16 v[64:67], v[214:217], v[246:249], v[64:67]
	s_barrier
; #define PG8_STAGE(bufoff, gbase, voff) do { _Pragma("unroll") for (int _i = 0; _i < 2; ++_i) \
;         __builtin_amdgcn_global_load_lds((const unsigned*)((const char*)(gbase) + (voff)[_i]), (PG8_LAS unsigned*)(lds + (bufoff) + ldsw + _i * 8192), 16, 0, 0); } while (0)
; #define PG8_LDA(dst, b, h) do { _Pragma("unroll") for (int m = 0; m < 4; ++m) _Pragma("unroll") for (int k = 0; k < 2; ++k) dst[m][k] = *(const PG8_LAS bf16x8*)(lds + PG8_SA(b, h) + aoff + m * 2048 + k * 1024); } while (0)
; #define PG8_MMA(ai, bj, At, Bt) do { __builtin_amdgcn_s_setprio(1); _Pragma("unroll") for (int m = 0; m < 4; ++m) _Pragma("unroll") for (int n = 0; n < 2; ++n) _Pragma("unroll") for (int k = 0; k < 2; ++k) \
;         acc[ai][bj][m][n] = __builtin_amdgcn_mfma_f32_16x16x32_bf16(Bt[n][k], At[m][k], acc[ai][bj][m][n], 0, 0, 0); __builtin_amdgcn_s_setprio(0); } while (0)
; #define PG8_WAIT_V(n) asm volatile("s_waitcnt vmcnt(" #n ")" ::: "memory")
; #define PG8_WAIT_L(n) asm volatile("s_waitcnt lgkmcnt(" #n ")" ::: "memory")
; #define PG8_BAR __builtin_amdgcn_s_barrier()
; #define PG8_SCHED __builtin_amdgcn_sched_barrier(0)
; template <class Epi, class Sched, bool ALIGN_EPI = false, bool SP2 = false>
; __device__ __forceinline__ void gemm_phase(PG8_LAS unsigned char* lds, const Gemm g, const Sched& S, const Epi& E) {
;     ...
;             PG8_LDA(At, 1, 1); PG8_STAGE(PG8_SB(1, 0), b3, voffB); PG8_STAGE(PG8_SB(1, 1), b3 + hstep, voffB); PG8_STAGE(PG8_SA(1, 0), a3, voffA);
;             PG8_WAIT_V(8); PG8_WAIT_L(0); PG8_BAR; PG8_MMA(1, 0, At, B0); PG8_MMA(1, 1, At, B1); PG8_BAR; PG8_SCHED;
	s_setprio 0
	s_add_i32 s6, s59, s24
	v_lshl_add_u64 v[172:173], v[172:173], 0, s[94:95]
	s_mov_b32 m0, s6
	ds_read_b128 v[218:221], v199 offset:49152
	ds_read_b128 v[222:225], v199 offset:50176
	ds_read_b128 v[226:229], v199 offset:51200
	ds_read_b128 v[230:233], v199 offset:52224
	ds_read_b128 v[234:237], v199 offset:53248
	ds_read_b128 v[238:241], v199 offset:54272
	ds_read_b128 v[242:245], v199 offset:55296
	ds_read_b128 v[246:249], v199 offset:56320
	global_load_lds_dwordx4 v[172:173], off
	s_add_i32 m0, s6, 0x2000
	s_add_u32 s0, s0, 0x40080
	v_lshl_add_u64 v[172:173], v[184:185], 0, s[94:95]
	s_addc_u32 s1, s1, 0
	s_add_i32 s6, s60, s24
	global_load_lds_dwordx4 v[172:173], off
	v_lshl_add_u64 v[172:173], s[0:1], 0, v[154:155]
	s_mov_b32 m0, s6
	s_nop 0
	global_load_lds_dwordx4 v[172:173], off
	v_lshl_add_u64 v[172:173], s[0:1], 0, v[150:151]
	s_add_i32 m0, s6, 0x2000
	s_nop 0
	global_load_lds_dwordx4 v[172:173], off
	v_lshl_add_u64 v[172:173], v[186:187], 0, s[94:95]
	s_mov_b32 m0, s29
	s_nop 0
	global_load_lds_dwordx4 v[172:173], off
	v_lshl_add_u64 v[172:173], v[188:189], 0, s[94:95]
	s_mov_b32 m0, s30
	s_nop 0
	global_load_lds_dwordx4 v[172:173], off
	s_waitcnt vmcnt(8)
	s_waitcnt lgkmcnt(0)
	.p2alignl 3, 3212836864
	s_setprio 1
	s_barrier
	v_mfma_f32_16x16x32_bf16 v[60:63], v[132:135], v[218:221], v[60:63]
	v_mfma_f32_16x16x32_bf16 v[56:59], v[140:143], v[218:221], v[56:59]
	v_mfma_f32_16x16x32_bf16 v[44:47], v[132:135], v[226:229], v[44:47]
	v_mfma_f32_16x16x32_bf16 v[40:43], v[140:143], v[226:229], v[40:43]
	v_mfma_f32_16x16x32_bf16 v[28:31], v[132:135], v[234:237], v[28:31]
	v_mfma_f32_16x16x32_bf16 v[24:27], v[140:143], v[234:237], v[24:27]
	v_mfma_f32_16x16x32_bf16 v[12:15], v[132:135], v[242:245], v[12:15]
	v_mfma_f32_16x16x32_bf16 v[8:11], v[140:143], v[242:245], v[8:11]
	v_mfma_f32_16x16x32_bf16 v[60:63], v[136:139], v[222:225], v[60:63]
	v_mfma_f32_16x16x32_bf16 v[56:59], v[180:183], v[222:225], v[56:59]
	v_mfma_f32_16x16x32_bf16 v[44:47], v[136:139], v[230:233], v[44:47]
	v_mfma_f32_16x16x32_bf16 v[40:43], v[180:183], v[230:233], v[40:43]
	v_mfma_f32_16x16x32_bf16 v[28:31], v[136:139], v[238:241], v[28:31]
	v_mfma_f32_16x16x32_bf16 v[24:27], v[180:183], v[238:241], v[24:27]
	v_mfma_f32_16x16x32_bf16 v[12:15], v[136:139], v[246:249], v[12:15]
	v_mfma_f32_16x16x32_bf16 v[8:11], v[180:183], v[246:249], v[8:11]
	s_setprio 0
	s_setprio 1
	v_mfma_f32_16x16x32_bf16 v[52:55], v[202:205], v[218:221], v[52:55]
	v_mfma_f32_16x16x32_bf16 v[48:51], v[210:213], v[218:221], v[48:51]
	v_mfma_f32_16x16x32_bf16 v[36:39], v[202:205], v[226:229], v[36:39]
	v_mfma_f32_16x16x32_bf16 v[32:35], v[210:213], v[226:229], v[32:35]
	v_mfma_f32_16x16x32_bf16 v[20:23], v[202:205], v[234:237], v[20:23]
	v_mfma_f32_16x16x32_bf16 v[16:19], v[210:213], v[234:237], v[16:19]
	v_mfma_f32_16x16x32_bf16 v[4:7], v[202:205], v[242:245], v[4:7]
	v_mfma_f32_16x16x32_bf16 v[0:3], v[210:213], v[242:245], v[0:3]
	v_mfma_f32_16x16x32_bf16 v[52:55], v[206:209], v[222:225], v[52:55]
	v_mfma_f32_16x16x32_bf16 v[48:51], v[214:217], v[222:225], v[48:51]
	v_mfma_f32_16x16x32_bf16 v[36:39], v[206:209], v[230:233], v[36:39]
	v_mfma_f32_16x16x32_bf16 v[32:35], v[214:217], v[230:233], v[32:35]
	v_mfma_f32_16x16x32_bf16 v[20:23], v[206:209], v[238:241], v[20:23]
	v_mfma_f32_16x16x32_bf16 v[16:19], v[214:217], v[238:241], v[16:19]
	v_mfma_f32_16x16x32_bf16 v[4:7], v[206:209], v[246:249], v[4:7]
	v_mfma_f32_16x16x32_bf16 v[0:3], v[214:217], v[246:249], v[0:3]
	s_barrier
	s_setprio 0
	s_add_i32 s58, s58, 2
	s_add_u32 s4, s4, 0x100
	s_addc_u32 s5, s5, 0
	s_add_u32 s56, s56, 0x100
	s_addc_u32 s57, s57, 0
	s_cmp_gt_u32 s58, 13
	s_cbranch_scc1 .LBB0_247

; #define PG8_BAR __builtin_amdgcn_s_barrier()
; template <class Epi, class Sched, bool ALIGN_EPI = false, bool SP2 = false>
; __device__ __forceinline__ void gemm_phase(PG8_LAS unsigned char* lds, const Gemm g, const Sched& S, const Epi& E) {
;     ...
;         if constexpr (ALIGN_EPI) { if (wr == 0) PG8_BAR; }
;         if constexpr (!Epi::AFTER_DRAIN) { E(acc, cur, wr, wc, fr, fq); S.done(cur); }
;         if (!has_next) break;
;         { typename Epi::Pre pren = E.issue(nxt, wr, wc, fr, fq); E.finish(acc, pren); }
;         cur = nxt; cA = nA; cB = nB; ++ui;
;         if constexpr (ALIGN_EPI) { if (wr == 1) PG8_BAR; }
.LBB0_1022:
	s_andn2_b64 vcc, exec, s[40:41]
	s_cbranch_vccnz .LBB0_239
	s_branch .LBB0_239

; #define PG8_STAGE(bufoff, gbase, voff) do { _Pragma("unroll") for (int _i = 0; _i < 2; ++_i) \
;         __builtin_amdgcn_global_load_lds((const unsigned*)((const char*)(gbase) + (voff)[_i]), (PG8_LAS unsigned*)(lds + (bufoff) + ldsw + _i * 8192), 16, 0, 0); } while (0)
; #define PG8_LDA(dst, b, h) do { _Pragma("unroll") for (int m = 0; m < 4; ++m) _Pragma("unroll") for (int k = 0; k < 2; ++k) dst[m][k] = *(const PG8_LAS bf16x8*)(lds + PG8_SA(b, h) + aoff + m * 2048 + k * 1024); } while (0)
; #define PG8_LDB(dst, b, h) do { _Pragma("unroll") for (int n = 0; n < 2; ++n) _Pragma("unroll") for (int k = 0; k < 2; ++k) dst[n][k] = *(const PG8_LAS bf16x8*)(lds + PG8_SB(b, h) + boff + n * 2048 + k * 1024); } while (0)
; #define PG8_WAIT_V(n) asm volatile("s_waitcnt vmcnt(" #n ")" ::: "memory")
; #define PG8_WAIT_L(n) asm volatile("s_waitcnt lgkmcnt(" #n ")" ::: "memory")
; template <class Epi, class Sched, bool ALIGN_EPI = false, bool SP2 = false>
; __device__ __forceinline__ void gemm_phase(PG8_LAS unsigned char* lds, const Gemm g, const Sched& S, const Epi& E) {
;     ...
;         const bool has_next = S.next(ui + 1, nxt);
;         const char* nA = has_next ? (const char*)g.A + (size_t)nxt.pm * tstep : cA; const char* nB = has_next ? (const char*)g.Bt + (size_t)nxt.pn * tstep : cB;
;         for (int t = 0; t < nt; t += 2) {
;             const bool last = (t == nt - 2);
;             const char* a1 = cA + (size_t)(t + 1) * kstep;
;             const char* a2 = last ? nA : cA + (size_t)(t + 2) * kstep; const char* b2 = last ? nB : cB + (size_t)(t + 2) * kstep;
;             const char* a3 = a2 + kstep; const char* b3 = b2 + kstep;
;             if (last && has_next) S.a_ready(nxt);
;             if (last) E.pre(cur, wid, lane);
;             if constexpr (SP2) {
;             PG8_LDB(B0, 0, 0); PG8_LDB(B1, 0, 1); PG8_SCHED; PG8_LDA(At, 0, 0); PG8_STAGE(PG8_SA(1, 1), a1 + hstep, voffA);
;             PG8_WAIT_V(8); PG8_WAIT_L(0); PG8_BAR; PG8_MMA(0, 0, At, B0); PG8_MMA(0, 1, At, B1); PG8_BAR; PG8_SCHED;
;     __device__ __forceinline__ void pre(const pg8::Unit& u, int wid, int lane) const {
; #pragma unroll
;         for (int i = 0; i < 2; ++i) __builtin_amdgcn_global_load_lds((const unsigned*)(ssq + (size_t)(u.pm * 256 + wid * 32 + i * 16 + (lane >> 2)) * 16 + (lane & 3) * 4), (LAS unsigned*)(sl + (wid * 32 + i * 16) * 64), 16, 0, 0);
;     }
.LBB0_1646:
	s_ashr_i32 s47, s46, 31
	s_lshl_b64 s[6:7], s[46:47], 19
	s_add_u32 s48, s10, s6
	s_addc_u32 s49, s11, s7
	s_and_b64 s[6:7], s[36:37], exec
	s_cselect_b32 s39, s49, s5
	s_cselect_b32 s47, s48, s4
	s_ashr_i32 s45, s44, 31
	s_lshl_b64 s[6:7], s[44:45], 19
	s_add_u32 s50, s24, s6
	s_addc_u32 s51, s25, s7
	s_and_b64 s[6:7], s[36:37], exec
	s_cselect_b32 s53, s51, s1
	s_cselect_b32 s54, s50, s0
	s_lshl_b32 s45, s55, 8
	v_add_u32_e32 v0, s45, v167
	v_ashrrev_i32_e32 v1, 31, v0
	v_lshlrev_b64 v[2:3], 6, v[0:1]
	v_or_b32_e32 v0, 16, v0
	v_ashrrev_i32_e32 v1, 31, v0
	s_add_u32 s4, s4, 0x40080
	v_lshlrev_b64 v[0:1], 6, v[0:1]
	s_addc_u32 s5, s5, 0
	v_lshl_add_u64 v[128:129], v[156:157], 0, v[0:1]
	s_add_u32 s55, s0, 0x100
	v_lshl_add_u64 v[130:131], v[156:157], 0, v[2:3]
	s_addc_u32 s56, s1, 0
	s_mov_b32 s57, -2
	s_cmp_gt_u32 s35, 1
	s_cselect_b64 vcc, s[40:41], 0
	s_cbranch_vccz .Lgu_nostag
	s_barrier
.Lgu_nostag:
	s_branch .Lgu_peel
.LBB0_1647:
	s_add_u32 s6, s4, 0xfffc0080
	s_addc_u32 s7, s5, -1
	s_and_b64 s[0:1], s[0:1], exec
	s_cselect_b32 s7, s39, s7
	s_cselect_b32 s6, s47, s6
	s_cselect_b32 s1, s53, s56
	s_cselect_b32 s0, s54, s55
	s_cmp_eq_u32 s57, -2
	s_cselect_b32 vcc_lo, 1, 0
	s_cmp_gt_u32 s35, 1
	s_cselect_b32 vcc_lo, vcc_lo, 0
	s_add_i32 s58, 0, 0x10000
	v_add_u32_e32 v162, s58, v165
	s_add_i32 s60, 0, 0x14000
	ds_read_b128 v[132:135], v162
	ds_read_b128 v[136:139], v162 offset:1024
	ds_read_b128 v[140:143], v162 offset:2048
	ds_read_b128 v[180:183], v162 offset:3072
	v_add_u32_e32 v162, s60, v165
	ds_read_b128 v[200:203], v162
	ds_read_b128 v[204:207], v162 offset:1024
	ds_read_b128 v[208:211], v162 offset:2048
	ds_read_b128 v[212:215], v162 offset:3072
	v_lshl_add_u64 v[168:169], s[4:5], 0, v[158:159]
	s_add_i32 m0, s27, 0xc000
	ds_read_b128 v[216:219], v197
	ds_read_b128 v[220:223], v197 offset:1024
	ds_read_b128 v[224:227], v197 offset:2048
	ds_read_b128 v[228:231], v197 offset:3072
	ds_read_b128 v[232:235], v197 offset:4096
	ds_read_b128 v[236:239], v197 offset:5120
	ds_read_b128 v[240:243], v197 offset:6144
	ds_read_b128 v[244:247], v197 offset:7168
	global_load_lds_dwordx4 v[168:169], off
	v_lshl_add_u64 v[168:169], s[4:5], 0, v[160:161]
	s_add_i32 m0, s27, 0xe000
	s_nop 0
	global_load_lds_dwordx4 v[168:169], off
	s_waitcnt vmcnt(16)
	s_cmp_lg_u32 vcc_lo, 0
	s_cbranch_scc1 .Lgu_relaxed0
	s_waitcnt vmcnt(8)
